# NSA: K-fragment LDS reads of the fast path hoisted above the DMA issue block
# baseline (speedup 1.0000x reference)
; #define LAS __attribute__((address_space(3)))
; #define MFMA32(a, b, c) __builtin_amdgcn_mfma_f32_32x32x16_bf16((a), (b), (c), 0, 0, 0)
; DI f32x16 co_qk1(LAS unsigned char* st, const bf16x8 (&qf)[8], int ka_in) {
;     ...
;     __builtin_amdgcn_s_setprio(1);
; #pragma unroll
;     for (int ks = 0; ks < 8; ++ks) { const bf16x8 a = *(const LAS bf16x8*)(st + (ka ^ (32 * ks))); S = MFMA32(a, qf[ks], S); }
;     __builtin_amdgcn_s_setprio(0);
.LBB0_510:
	s_waitcnt lgkmcnt(0)
	s_barrier
	s_and_b32 s89, s76, 0xc000
	v_add_u32_e32 v252, s89, v162
	ds_read_b128 v[216:219], v252
	v_add_u32_e32 v252, s89, v164
	ds_read_b128 v[220:223], v252
	v_add_u32_e32 v252, s89, v165
	ds_read_b128 v[224:227], v252
	v_add_u32_e32 v252, s89, v166
	ds_read_b128 v[228:231], v252
	v_add_u32_e32 v252, s89, v167
	ds_read_b128 v[232:235], v252
	v_add_u32_e32 v252, s89, v168
	ds_read_b128 v[240:243], v252
	v_add_u32_e32 v252, s89, v169
	ds_read_b128 v[244:247], v252
	v_add_u32_e32 v252, s89, v170
	ds_read_b128 v[248:251], v252
	s_cmp_gt_i32 s77, s33
	s_cbranch_scc1 .LBB0_515
	v_cmp_gt_u32_e32 vcc, s46, v238
	v_readfirstlane_b32 s81, v238
	s_cbranch_vccnz .LBB0_513
	s_cmp_lt_u32 s81, 0x30000
	s_cselect_b32 s0, 0x4000, s51
	s_cselect_b32 s16, s50, 0x3c800000
	s_add_u32 s2, s73, s0
	s_addc_u32 s3, s74, 0
	s_movk_i32 s82, 0x7600
	s_movk_i32 s80, 0x1000
	s_mov_b64 s[8:9], s[16:17]
	s_mov_b64 s[40:41], s[20:21]
	s_branch .LBB0_514

; #define CO_STEP2(list, n, i) do { \
;     if ((n) - 1 - (i) >= 1) asm volatile("s_waitcnt vmcnt(2)" ::: "memory"); else asm volatile("s_waitcnt vmcnt(0)" ::: "memory"); \
;     asm volatile("s_waitcnt lgkmcnt(0)" ::: "memory"); __builtin_amdgcn_s_barrier(); asm volatile("" ::: "memory"); \
;     if ((i) + 2 < (n)) co_issue(P, ring, ((i) + 2) & 3, (list)[(i) + 2], b, g, wave, lane); } while (0)
; #define CO_PIPE(MODE, REL, KB, RS) do { const bool rel_ = (REL); LAS unsigned char* sp_ = ring + (i & 3) * 16384; f32x16 Sn_; \
;     if (rel_) Sn_ = co_qk1(sp_, qf, ka); \
;     if (pend) co_finish<MODE>(Sp, pst, pkb, st, tq, prs, vb, hh); \
;     pend = rel_; if (rel_) { Sp = Sn_; pst = sp_; pkb = (KB); prs = (RS); } } while (0)
; DI void nsa_block_item(const Params& P, unsigned char* smem_g, int b, int g, int tb, int tid_in) {
;     ...
;     for (i = 0; i < n2; ++i) {
;         CO_STEP2(list2, n2, i); const int kb_ = (int)(list2[i] & 0xffffu); const int j = kb_ >> 6;
;         CO_PIPE(1, ((Uw >> j) & 1u) && kb_ <= t0 + 3, kb_, (bool)((mysel >> j) & 1u));
.LBB0_541:
	s_waitcnt lgkmcnt(0)
	s_barrier
	s_and_b32 s89, s72, 0xc000
	v_add_u32_e32 v252, s89, v162
	ds_read_b128 v[216:219], v252
	v_add_u32_e32 v252, s89, v164
	ds_read_b128 v[220:223], v252
	v_add_u32_e32 v252, s89, v165
	ds_read_b128 v[224:227], v252
	v_add_u32_e32 v252, s89, v166
	ds_read_b128 v[228:231], v252
	v_add_u32_e32 v252, s89, v167
	ds_read_b128 v[232:235], v252
	v_add_u32_e32 v252, s89, v168
	ds_read_b128 v[240:243], v252
	v_add_u32_e32 v252, s89, v169
	ds_read_b128 v[244:247], v252
	v_add_u32_e32 v252, s89, v170
	ds_read_b128 v[248:251], v252
	s_cmp_lg_u32 s41, 0
	s_cbranch_scc1 .Lsel_pf_ok
	v_mov_b32_e32 v239, s71
	ds_read_b32 v238, v239 offset:8
	ds_read_b32 v237, v239
	s_waitcnt lgkmcnt(0)

; #define LAS __attribute__((address_space(3)))
; DI float xh_max(float x) { const unsigned u = __float_as_uint(x); const auto r = __builtin_amdgcn_permlane32_swap(u, u, false, false); return fmaxf(__uint_as_float(r[0]), __uint_as_float(r[1])); }
; DI float xh_sum(float x) { const unsigned u = __float_as_uint(x); const auto r = __builtin_amdgcn_permlane32_swap(u, u, false, false); return __uint_as_float(r[0]) + __uint_as_float(r[1]); }
; #define MFMA32(a, b, c) __builtin_amdgcn_mfma_f32_32x32x16_bf16((a), (b), (c), 0, 0, 0)
; DI f32x16 co_qk1(LAS unsigned char* st, const bf16x8 (&qf)[8], int ka_in) {
;     const int ka = ka_in;
;     f32x16 S;
; #pragma unroll
;     for (int i = 0; i < 16; ++i) S[i] = 0.f;
;     __builtin_amdgcn_s_setprio(1);
; #pragma unroll
;     for (int ks = 0; ks < 8; ++ks) { const bf16x8 a = *(const LAS bf16x8*)(st + (ka ^ (32 * ks))); S = MFMA32(a, qf[ks], S); }
;     __builtin_amdgcn_s_setprio(0);
;     return S;
; }
; template <int MODE>
; DI void co_finish(f32x16 S, LAS unsigned char* st, int key_base, AttnState& as, int tq, bool rowsel, int vb_in, int hh) {
;     const int vb = vb_in;
;     {
;         const int base = key_base + 4 * hh;
;         const int hi = (MODE == 0) ? (((tq - 31) >> 4) - base) : (tq - base);
;         const int lo = hi - 512;
; #pragma unroll
;         for (int i = 0; i < 16; ++i) { const int c = (i & 3) + 8 * (i >> 2); bool ok = (c <= hi); if (MODE == 2) ok = ok && (c > lo); if (MODE == 1) ok = ok && rowsel; S[i] = ok ? S[i] : -1e30f; }
;     }
;     float mx = S[0];
; #pragma unroll
;     for (int i = 1; i < 16; ++i) mx = fmaxf(mx, S[i]);
;     mx = xh_max(mx);
;     const float mxs = mx * SM_SCALE; const bool need = mxs > as.m + 8.f;
;     const float mnew = need ? mxs : as.m, muse = -fmaxf(mnew, -1e20f); float ps = 0.f;
; #pragma unroll
;     for (int i = 0; i < 16; ++i) { const float p = __builtin_amdgcn_exp2f(__builtin_fmaf(S[i], SM_SCALE, muse)); S[i] = p; ps += p; }
;     ps = xh_sum(ps);
;     if (__builtin_amdgcn_ballot_w64(need) != 0ull) {
;         const float alpha = __builtin_amdgcn_exp2f(as.m - mnew);
;         as.l *= alpha;
; #pragma unroll
;         for (int dt = 0; dt < 4; ++dt)
; #pragma unroll
;             for (int i = 0; i < 16; ++i) as.acc[dt][i] *= alpha;
;     }
;     as.l += ps; as.m = mnew;
.Lfast_sel:
	v_max_f32_e32 v0, v16, v17
	v_max3_f32 v0, v0, v18, v19
	v_max3_f32 v0, v0, v20, v21
	v_max3_f32 v0, v0, v22, v23
	s_waitcnt lgkmcnt(7)
	v_mfma_f32_32x32x16_bf16 v[96:111], v[216:219], v[112:115], 0
	v_max3_f32 v0, v0, v24, v25
	v_max3_f32 v0, v0, v26, v27
	v_max3_f32 v0, v0, v28, v29
	v_max3_f32 v0, v0, v30, v31
	v_mov_b32_e32 v15, v0
	v_add_u32_e32 v253, s62, v156
	v_add_u32_e32 v254, s62, v171
	v_permlane32_swap_b32_e32 v0, v15
	ds_read_b64 v[180:181], v253 offset:8192
	ds_read_b64 v[182:183], v254 offset:8192
	ds_read_b64 v[184:185], v253 offset:10240
	ds_read_b64 v[186:187], v254 offset:10240
	ds_read_b64 v[188:189], v253 offset:12288
	ds_read_b64 v[190:191], v254 offset:12288
	ds_read_b64 v[192:193], v253 offset:14336
	ds_read_b64 v[194:195], v254 offset:14336
	v_max_f32_e32 v0, v0, v15
	s_waitcnt lgkmcnt(14)
	v_mfma_f32_32x32x16_bf16 v[96:111], v[220:223], v[116:119], v[96:111]
	v_cndmask_b32_e64 v0, v153, v0, s[26:27]
	v_mul_f32_e32 v0, 0x3e0293ee, v0
	v_add_f32_e32 v15, 0x41000000, v175
	v_cmp_gt_f32_e32 vcc, v0, v15
	v_add_u32_e32 v255, s62, v172
	v_add_u32_e32 v214, s62, v173
	v_cndmask_b32_e32 v174, v175, v0, vcc
	v_max_f32_e32 v14, 0xe0ad78ec, v174
	v_mov_b32_e32 v13, 0x7149f2ca
	v_cndmask_b32_e64 v14, v13, v14, s[26:27]
	s_waitcnt lgkmcnt(13)
	v_mfma_f32_32x32x16_bf16 v[96:111], v[224:227], v[120:123], v[96:111]
	s_cbranch_vccz .Lfast_sel_nr
	v_sub_f32_e32 v175, v175, v174
	v_exp_f32_e32 v12, v175
	s_nop 0
	v_mul_f32_e32 v163, v163, v12
	v_pk_mul_f32 v[94:95], v[94:95], v[12:13] op_sel_hi:[1,0]
	v_pk_mul_f32 v[92:93], v[92:93], v[12:13] op_sel_hi:[1,0]
	v_pk_mul_f32 v[90:91], v[90:91], v[12:13] op_sel_hi:[1,0]
	v_pk_mul_f32 v[88:89], v[88:89], v[12:13] op_sel_hi:[1,0]
	v_pk_mul_f32 v[86:87], v[86:87], v[12:13] op_sel_hi:[1,0]
	v_pk_mul_f32 v[84:85], v[84:85], v[12:13] op_sel_hi:[1,0]
	v_pk_mul_f32 v[82:83], v[82:83], v[12:13] op_sel_hi:[1,0]
	v_pk_mul_f32 v[80:81], v[80:81], v[12:13] op_sel_hi:[1,0]
	v_pk_mul_f32 v[78:79], v[78:79], v[12:13] op_sel_hi:[1,0]
	v_pk_mul_f32 v[76:77], v[76:77], v[12:13] op_sel_hi:[1,0]
	v_pk_mul_f32 v[74:75], v[74:75], v[12:13] op_sel_hi:[1,0]
	v_pk_mul_f32 v[72:73], v[72:73], v[12:13] op_sel_hi:[1,0]
	v_pk_mul_f32 v[70:71], v[70:71], v[12:13] op_sel_hi:[1,0]
	v_pk_mul_f32 v[68:69], v[68:69], v[12:13] op_sel_hi:[1,0]
	v_pk_mul_f32 v[66:67], v[66:67], v[12:13] op_sel_hi:[1,0]
	v_pk_mul_f32 v[64:65], v[64:65], v[12:13] op_sel_hi:[1,0]
	v_pk_mul_f32 v[62:63], v[62:63], v[12:13] op_sel_hi:[1,0]
	v_pk_mul_f32 v[60:61], v[60:61], v[12:13] op_sel_hi:[1,0]
	v_pk_mul_f32 v[58:59], v[58:59], v[12:13] op_sel_hi:[1,0]
	v_pk_mul_f32 v[56:57], v[56:57], v[12:13] op_sel_hi:[1,0]
	v_pk_mul_f32 v[54:55], v[54:55], v[12:13] op_sel_hi:[1,0]
	v_pk_mul_f32 v[52:53], v[52:53], v[12:13] op_sel_hi:[1,0]
	v_pk_mul_f32 v[50:51], v[50:51], v[12:13] op_sel_hi:[1,0]
	v_pk_mul_f32 v[48:49], v[48:49], v[12:13] op_sel_hi:[1,0]
	v_pk_mul_f32 v[46:47], v[46:47], v[12:13] op_sel_hi:[1,0]
	v_pk_mul_f32 v[44:45], v[44:45], v[12:13] op_sel_hi:[1,0]
	v_pk_mul_f32 v[42:43], v[42:43], v[12:13] op_sel_hi:[1,0]
	v_pk_mul_f32 v[40:41], v[40:41], v[12:13] op_sel_hi:[1,0]
	v_pk_mul_f32 v[38:39], v[38:39], v[12:13] op_sel_hi:[1,0]
	v_pk_mul_f32 v[36:37], v[36:37], v[12:13] op_sel_hi:[1,0]
	v_pk_mul_f32 v[34:35], v[34:35], v[12:13] op_sel_hi:[1,0]
	v_pk_mul_f32 v[32:33], v[32:33], v[12:13] op_sel_hi:[1,0]

; #define LAS __attribute__((address_space(3)))
; DI float xh_max(float x) { const unsigned u = __float_as_uint(x); const auto r = __builtin_amdgcn_permlane32_swap(u, u, false, false); return fmaxf(__uint_as_float(r[0]), __uint_as_float(r[1])); }
; DI float xh_sum(float x) { const unsigned u = __float_as_uint(x); const auto r = __builtin_amdgcn_permlane32_swap(u, u, false, false); return __uint_as_float(r[0]) + __uint_as_float(r[1]); }
; #define MFMA32(a, b, c) __builtin_amdgcn_mfma_f32_32x32x16_bf16((a), (b), (c), 0, 0, 0)
; DI f32x16 co_qk1(LAS unsigned char* st, const bf16x8 (&qf)[8], int ka_in) {
;     const int ka = ka_in;
;     f32x16 S;
; #pragma unroll
;     for (int i = 0; i < 16; ++i) S[i] = 0.f;
;     __builtin_amdgcn_s_setprio(1);
; #pragma unroll
;     for (int ks = 0; ks < 8; ++ks) { const bf16x8 a = *(const LAS bf16x8*)(st + (ka ^ (32 * ks))); S = MFMA32(a, qf[ks], S); }
;     __builtin_amdgcn_s_setprio(0);
;     return S;
; }
; template <int MODE>
; DI void co_finish(f32x16 S, LAS unsigned char* st, int key_base, AttnState& as, int tq, bool rowsel, int vb_in, int hh) {
;     const int vb = vb_in;
;     {
;         const int base = key_base + 4 * hh;
;         const int hi = (MODE == 0) ? (((tq - 31) >> 4) - base) : (tq - base);
;         const int lo = hi - 512;
; #pragma unroll
;         for (int i = 0; i < 16; ++i) { const int c = (i & 3) + 8 * (i >> 2); bool ok = (c <= hi); if (MODE == 2) ok = ok && (c > lo); if (MODE == 1) ok = ok && rowsel; S[i] = ok ? S[i] : -1e30f; }
;     }
;     float mx = S[0];
; #pragma unroll
;     for (int i = 1; i < 16; ++i) mx = fmaxf(mx, S[i]);
;     mx = xh_max(mx);
;     const float mxs = mx * SM_SCALE; const bool need = mxs > as.m + 8.f;
;     const float mnew = need ? mxs : as.m, muse = -fmaxf(mnew, -1e20f); float ps = 0.f;
; #pragma unroll
;     for (int i = 0; i < 16; ++i) { const float p = __builtin_amdgcn_exp2f(__builtin_fmaf(S[i], SM_SCALE, muse)); S[i] = p; ps += p; }
;     ps = xh_sum(ps);
;     if (__builtin_amdgcn_ballot_w64(need) != 0ull) {
;         const float alpha = __builtin_amdgcn_exp2f(as.m - mnew);
;         as.l *= alpha;
; #pragma unroll
;         for (int dt = 0; dt < 4; ++dt)
; #pragma unroll
;             for (int i = 0; i < 16; ++i) as.acc[dt][i] *= alpha;
;     }
;     as.l += ps; as.m = mnew;
.Lfast_win:
	v_max_f32_e32 v0, v16, v17
	v_max3_f32 v0, v0, v18, v19
	v_max3_f32 v0, v0, v20, v21
	v_max3_f32 v0, v0, v22, v23
	s_waitcnt lgkmcnt(7)
	v_mfma_f32_32x32x16_bf16 v[96:111], v[216:219], v[112:115], 0
	v_max3_f32 v0, v0, v24, v25
	v_max3_f32 v0, v0, v26, v27
	v_max3_f32 v0, v0, v28, v29
	v_max3_f32 v0, v0, v30, v31
	v_mov_b32_e32 v15, v0
	v_add_u32_e32 v253, s62, v156
	v_add_u32_e32 v254, s62, v171
	v_permlane32_swap_b32_e32 v0, v15
	ds_read_b64 v[180:181], v253 offset:8192
	ds_read_b64 v[182:183], v254 offset:8192
	ds_read_b64 v[184:185], v253 offset:10240
	ds_read_b64 v[186:187], v254 offset:10240
	ds_read_b64 v[188:189], v253 offset:12288
	ds_read_b64 v[190:191], v254 offset:12288
	ds_read_b64 v[192:193], v253 offset:14336
	ds_read_b64 v[194:195], v254 offset:14336
	v_max_f32_e32 v0, v0, v15
	s_waitcnt lgkmcnt(14)
	v_mfma_f32_32x32x16_bf16 v[96:111], v[220:223], v[116:119], v[96:111]
	v_mul_f32_e32 v0, 0x3e0293ee, v0
	v_add_f32_e32 v15, 0x41000000, v177
	v_cmp_gt_f32_e32 vcc, v0, v15
	v_add_u32_e32 v255, s62, v172
	v_add_u32_e32 v214, s62, v173
	v_cndmask_b32_e32 v176, v177, v0, vcc
	v_max_f32_e32 v14, 0xe0ad78ec, v176
	s_waitcnt lgkmcnt(13)
	v_mfma_f32_32x32x16_bf16 v[96:111], v[224:227], v[120:123], v[96:111]
	s_cbranch_vccz .Lfast_win_nr
	v_sub_f32_e32 v177, v177, v176
	v_exp_f32_e32 v12, v177
	s_nop 0
	v_mul_f32_e32 v175, v175, v12
	v_pk_mul_f32 v[94:95], v[94:95], v[12:13] op_sel_hi:[1,0]
	v_pk_mul_f32 v[92:93], v[92:93], v[12:13] op_sel_hi:[1,0]
	v_pk_mul_f32 v[90:91], v[90:91], v[12:13] op_sel_hi:[1,0]
	v_pk_mul_f32 v[88:89], v[88:89], v[12:13] op_sel_hi:[1,0]
	v_pk_mul_f32 v[86:87], v[86:87], v[12:13] op_sel_hi:[1,0]
	v_pk_mul_f32 v[84:85], v[84:85], v[12:13] op_sel_hi:[1,0]
	v_pk_mul_f32 v[82:83], v[82:83], v[12:13] op_sel_hi:[1,0]
	v_pk_mul_f32 v[80:81], v[80:81], v[12:13] op_sel_hi:[1,0]
	v_pk_mul_f32 v[78:79], v[78:79], v[12:13] op_sel_hi:[1,0]
	v_pk_mul_f32 v[76:77], v[76:77], v[12:13] op_sel_hi:[1,0]
	v_pk_mul_f32 v[74:75], v[74:75], v[12:13] op_sel_hi:[1,0]
	v_pk_mul_f32 v[72:73], v[72:73], v[12:13] op_sel_hi:[1,0]
	v_pk_mul_f32 v[70:71], v[70:71], v[12:13] op_sel_hi:[1,0]
	v_pk_mul_f32 v[68:69], v[68:69], v[12:13] op_sel_hi:[1,0]
	v_pk_mul_f32 v[66:67], v[66:67], v[12:13] op_sel_hi:[1,0]
	v_pk_mul_f32 v[64:65], v[64:65], v[12:13] op_sel_hi:[1,0]
	v_pk_mul_f32 v[62:63], v[62:63], v[12:13] op_sel_hi:[1,0]
	v_pk_mul_f32 v[60:61], v[60:61], v[12:13] op_sel_hi:[1,0]
	v_pk_mul_f32 v[58:59], v[58:59], v[12:13] op_sel_hi:[1,0]
	v_pk_mul_f32 v[56:57], v[56:57], v[12:13] op_sel_hi:[1,0]
	v_pk_mul_f32 v[54:55], v[54:55], v[12:13] op_sel_hi:[1,0]
	v_pk_mul_f32 v[52:53], v[52:53], v[12:13] op_sel_hi:[1,0]
	v_pk_mul_f32 v[50:51], v[50:51], v[12:13] op_sel_hi:[1,0]
	v_pk_mul_f32 v[48:49], v[48:49], v[12:13] op_sel_hi:[1,0]
	v_pk_mul_f32 v[46:47], v[46:47], v[12:13] op_sel_hi:[1,0]
	v_pk_mul_f32 v[44:45], v[44:45], v[12:13] op_sel_hi:[1,0]
	v_pk_mul_f32 v[42:43], v[42:43], v[12:13] op_sel_hi:[1,0]
	v_pk_mul_f32 v[40:41], v[40:41], v[12:13] op_sel_hi:[1,0]
	v_pk_mul_f32 v[38:39], v[38:39], v[12:13] op_sel_hi:[1,0]
	v_pk_mul_f32 v[36:37], v[36:37], v[12:13] op_sel_hi:[1,0]
	v_pk_mul_f32 v[34:35], v[34:35], v[12:13] op_sel_hi:[1,0]
	v_pk_mul_f32 v[32:33], v[32:33], v[12:13] op_sel_hi:[1,0]
